# adds: NA K/V staging task remap (kk = tid&255, role = tid>>8): waves 0-3 normalise K, waves 4-7 transpose V, no intra-wave divergence
# baseline (speedup 1.0000x reference)
; #define NA_LOAD(count_, GROW_EXPR) do { const int kk = tid >> 1, role = tid & 1; if (kk < (count_)) { const size_t grow = (size_t)(GROW_EXPR); \
;         GAS const v4u* src = (GAS const v4u*)(P + grow * NA_N + (role ? 2 * DM : DM) + h * 32); \
;         _Pragma("unroll") for (int t_ = 0; t_ < 4; ++t_) x[t_] = src[t_]; } } while (0)
; __device__ __forceinline__ void phase_na2(Frame& F, bool ctx_out, bool dry = false) {
;     ...
;         NA_LOAD(256, b * TCX + kk); NA_STORE(256, 768 + kk);
.LBB0_1589:
	s_or_b64 exec, exec, s[0:1]
	v_and_b32_e32 v147, 0xff, v58
	s_movk_i32 s0, 0x100
	v_cmp_gt_i32_e64 s[4:5], s0, v147
	s_movk_i32 s0, 0xff
	v_cmp_lt_i32_e32 vcc, s0, v147
	s_and_saveexec_b64 s[0:1], vcc
	s_xor_b64 s[0:1], exec, s[0:1]
	s_lshl_b32 s16, s9, 5
	s_or_saveexec_b64 s[0:1], s[0:1]
	s_ashr_i32 s8, s47, 6
	v_lshrrev_b32_e32 v59, 8, v58
	s_lshl_b32 s18, s8, 8
	v_mov_b64_e32 v[64:65], s[16:17]
	s_xor_b64 exec, exec, s[0:1]
	s_cbranch_execz .LBB0_1601
	v_add_u32_e32 v0, s18, v147
	v_mov_b64_e32 v[34:35], s[10:11]
	v_cmp_eq_u32_e32 vcc, 0, v59
	v_mad_i64_i32 v[34:35], s[2:3], v0, s41, v[34:35]
	s_nop 0
	v_cndmask_b32_e32 v0, v143, v144, vcc
	v_lshlrev_b32_e32 v0, 1, v0
	v_lshl_add_u64 v[34:35], v[34:35], 0, v[0:1]
	s_lshl_b32 s16, s9, 6
	v_lshl_add_u64 v[46:47], v[34:35], 0, s[16:17]
	global_load_dwordx4 v[42:45], v[46:47], off offset:48
	global_load_dwordx4 v[34:37], v[46:47], off offset:32
	global_load_dwordx4 v[38:41], v[46:47], off offset:16
	s_nop 0
	global_load_dwordx4 v[46:49], v[46:47], off
	v_cmp_ne_u32_e32 vcc, 0, v59
	v_add_u32_e32 v51, 0x300, v147
	s_and_saveexec_b64 s[2:3], vcc
	s_xor_b64 s[2:3], exec, s[2:3]
	s_cbranch_execz .LBB0_1594
	v_lshl_add_u32 v51, v51, 1, 0
	v_add_u32_e32 v52, 0x14000, v51
	s_waitcnt vmcnt(0)
	ds_write_b16 v52, v46
	v_add_u32_e32 v52, 0x14810, v51
	ds_write_b16_d16_hi v52, v46
	v_add_u32_e32 v46, 0x15020, v51
	ds_write_b16 v46, v47
	v_add_u32_e32 v46, 0x15830, v51
	ds_write_b16_d16_hi v46, v47
	v_add_u32_e32 v46, 0x16040, v51
	ds_write_b16 v46, v48
	v_add_u32_e32 v46, 0x16850, v51
	ds_write_b16_d16_hi v46, v48
	v_add_u32_e32 v46, 0x17060, v51
	ds_write_b16 v46, v49
	v_add_u32_e32 v46, 0x17870, v51
	ds_write_b16_d16_hi v46, v49
	v_add_u32_e32 v46, 0x18080, v51
	ds_write_b16 v46, v38
	v_add_u32_e32 v46, 0x18890, v51
	ds_write_b16_d16_hi v46, v38
	v_add_u32_e32 v38, 0x190a0, v51
	ds_write_b16 v38, v39
	v_add_u32_e32 v38, 0x198b0, v51
	ds_write_b16_d16_hi v38, v39
	v_add_u32_e32 v38, 0x1a0c0, v51
	ds_write_b16 v38, v40
	v_add_u32_e32 v38, 0x1a8d0, v51
	ds_write_b16_d16_hi v38, v40
	v_add_u32_e32 v38, 0x1b0e0, v51
	ds_write_b16 v38, v41
	v_add_u32_e32 v38, 0x1b8f0, v51
	ds_write_b16_d16_hi v38, v41
	v_add_u32_e32 v38, 0x1c100, v51
	ds_write_b16 v38, v34
	v_add_u32_e32 v38, 0x1c910, v51
	ds_write_b16_d16_hi v38, v34
	v_add_u32_e32 v34, 0x1d120, v51
	ds_write_b16 v34, v35
	v_add_u32_e32 v34, 0x1d930, v51
	ds_write_b16_d16_hi v34, v35
	v_add_u32_e32 v34, 0x1e140, v51
	ds_write_b16 v34, v36
	v_add_u32_e32 v34, 0x1e950, v51
	ds_write_b16_d16_hi v34, v36
	v_add_u32_e32 v34, 0x1f160, v51
	ds_write_b16 v34, v37
	v_add_u32_e32 v34, 0x1f970, v51
	ds_write_b16_d16_hi v34, v37
	v_add_u32_e32 v34, 0x20180, v51
	ds_write_b16 v34, v42
	v_add_u32_e32 v34, 0x20990, v51
	ds_write_b16_d16_hi v34, v42
	v_add_u32_e32 v34, 0x211a0, v51
	ds_write_b16 v34, v43
	v_add_u32_e32 v34, 0x219b0, v51
	ds_write_b16_d16_hi v34, v43
	v_add_u32_e32 v34, 0x221c0, v51
	ds_write_b16 v34, v44
	v_add_u32_e32 v34, 0x229d0, v51
	ds_write_b16_d16_hi v34, v44
	v_add_u32_e32 v34, 0x231e0, v51
	ds_write_b16 v34, v45
	v_add_u32_e32 v34, 0x239f0, v51
	ds_write_b16_d16_hi v34, v45

; #define LDS_BARRIER() do { asm volatile("s_waitcnt lgkmcnt(0)" ::: "memory"); __builtin_amdgcn_s_barrier(); asm volatile("" ::: "memory"); } while (0)
; #define NA_LOAD(count_, GROW_EXPR) do { const int kk = tid >> 1, role = tid & 1; if (kk < (count_)) { const size_t grow = (size_t)(GROW_EXPR); \
;         GAS const v4u* src = (GAS const v4u*)(P + grow * NA_N + (role ? 2 * DM : DM) + h * 32); \
;         _Pragma("unroll") for (int t_ = 0; t_ < 4; ++t_) x[t_] = src[t_]; } } while (0)
; __device__ __forceinline__ void phase_na2(Frame& F, bool ctx_out, bool dry = false) {
;     ...
;         v4u qn = NA_QLOAD(ROWS_C + b * TL + (wave >> 2) * 64 + (wave & 3) * 16);
;         NA_STORE(256, 256 + kk);
;         int staged_hi = 7;
; #pragma unroll 1
;         for (int rg = 0; rg < 8; ++rg) {
;             int nhi = 4 * (rg + 1) - 1; nhi = nhi > 24 ? 24 : nhi; nhi += 7;
;             const int r1 = staged_hi + 1, ncnt = (rg < 7) ? (nhi - staged_hi) * 64 : 0;
;             NA_LOAD(ncnt, ROWS_C + b * TL + r1 * 64 + kk);
;             LDS_BARRIER();
;             {
; #pragma unroll 1
;                 for (int qb = wave; qb < 16; qb += 8) { const int r = rg * 4 + (qb >> 2), cb = qb & 3; const v4u qc = qn;
;                     { const bool more = qb + 8 < 16; const int rgn = more ? rg : rg + 1, qbn = more ? qb + 8 : wave;
;                       if (more || rg < 7) qn = NA_QLOAD(ROWS_C + b * TL + (rgn * 4 + (qbn >> 2)) * 64 + (qbn & 3) * 16); }
;                     na_qblock(P, Oo, KI, VTI, bias, qg, h, ROWS_C + b * TL + r * 64 + cb * 16, true, r, cb, lane, dry, qc, tbl, tbl_d); }
;             }
;             LDS_BARRIER();
;             NA_STORE(ncnt, ((r1 + (kk >> 6)) % 12) * 64 + (kk & 63));
.LBB0_1613:
	s_or_b64 exec, exec, s[0:1]
	v_cmp_eq_u32_e32 vcc, 0, v59
	s_add_i32 s0, 0, 0x14000
	v_mad_u32_u24 v156, v148, s43, v71
	v_cndmask_b32_e32 v0, v145, v143, vcc
	v_lshl_add_u64 v[34:35], s[10:11], 0, v[0:1]
	v_lshl_add_u64 v[128:129], v[34:35], 0, v[62:63]
	v_add_u32_e32 v34, 12, v149
	v_cmp_eq_u32_e32 vcc, 0, v70
	v_add_u32_e32 v151, s16, v147
	s_mov_b32 s51, 0
	v_cndmask_b32_e32 v34, v34, v149, vcc
	v_ashrrev_i32_e32 v35, 31, v34
	v_cmp_ne_u32_e64 s[4:5], 0, v59
	v_or_b32_e32 v0, s16, v148
	v_lshl_add_u32 v152, v72, 5, s40
	v_add_u32_e32 v153, 0, v73
	s_mov_b32 s48, 7
	v_bfe_u32 v154, v58, 6, 2
	v_and_b32_e32 v155, 63, v58
	v_add_u32_e32 v157, s0, v156
	v_lshl_add_u64 v[130:131], v[34:35], 1, v[60:61]
	v_mov_b32_e32 v158, 0xffffff9c
